# gen12: gen9 + cross-half row-max exchange only on the rare rescale path (fast-path test uses the per-lane partial max)
# speedup vs baseline: 1.0289x; 1.0073x over previous
; DEVINL void pv_psm(f32x16* o, const VFrag& f, const i32x8& pa, f32x16& lsum, const i32x8& ones8,
;                    f32x16& p0, f32x16& p1, float& m_reg, float& mn, float& alpha, int kvalid, int hi) {
;   constexpr float C = MLA_SCALE * 1.4426950408889634f;
;     ...
;   if (kvalid < 64) {
; #pragma unroll
;     for (int r = 0; r < 16; ++r) { if (crow(r, hi) >= kvalid) p0[r] = -1e30f; if (32 + crow(r, hi) >= kvalid) p1[r] = -1e30f; }
;   }
;   PVM(0);
;   float pmax = p0[0];
; #pragma unroll
;   for (int r = 1; r < 16; ++r) pmax = fmaxf(pmax, p0[r]);
;   SBAR();
;   PVM(1);
; #pragma unroll
;   for (int r = 0; r < 16; ++r) pmax = fmaxf(pmax, p1[r]);
;   { auto rr = __builtin_amdgcn_permlane32_swap(__float_as_uint(pmax), __float_as_uint(pmax), false, false);
;     pmax = fmaxf(__uint_as_float(rr[0]), __uint_as_float(rr[1])); }
;   SBAR();
;   PVM(2);
;   if (__builtin_expect(__all(pmax - m_reg <= THR / MLA_SCALE), 1)) { mn = m_reg; alpha = 1.f; }
;   else { mn = fmaxf(m_reg, pmax); alpha = __builtin_amdgcn_exp2f((m_reg - mn) * C); m_reg = mn; }
;   const float mnC = PSHIFT - mn * C;
;   const f32x2 C2 = {C, C}, M2 = {mnC, mnC};
; #pragma unroll
;   for (int r = 0; r < 16; r += 2) { f32x2 v = {p0[r], p0[r + 1]}; v = __builtin_elementwise_fma(v, C2, M2); p0[r] = v[0]; p0[r + 1] = v[1]; }
;   SBAR();
;   PVM(3);
; #pragma unroll
;   for (int r = 0; r < 16; r += 2) { f32x2 v = {p1[r], p1[r + 1]}; v = __builtin_elementwise_fma(v, C2, M2); p1[r] = v[0]; p1[r + 1] = v[1]; }
; #pragma unroll
;   for (int r = 0; r < 8; ++r) p0[r] = __builtin_amdgcn_exp2f(p0[r]);
;   SBAR();
;   lsum = MFMA8(ones8, pa, (f32x16{}));
; #pragma unroll
;   for (int r = 8; r < 16; ++r) p0[r] = __builtin_amdgcn_exp2f(p0[r]);
; DEVINL void mla_block(const Params& p, const bf16_t* __restrict__ Qn, const bf16_t* __restrict__ Qr, const char* __restrict__ K8, const char* __restrict__ Kp8,
;                       const char* __restrict__ V8, const bf16_t* __restrict__ Gb, bf16_t* __restrict__ Yb, char* lds, int pos0) {
;     ...
;   for (int j = 1; j + 1 < NT; j += 2) {
;     ISSUE_K(j + 2); ISSUE_K(j + 3); ISSUE_V(j + 1); ISSUE_V(j + 2); SBAR();
;     qkt<true>(pB0, pB1, KS(j), q8, r32, hi, pA1);
;     pv_load(vf, VS(j - 1), r32, hi); SBAR();
;     finishSM<true>(pA0, pA1, alA, l_reg, pa); SBAR();
;     pv_psm(o, vf, pa, lsum, ones8, pB0, pB1, m_reg, mnB, alB, 64, hi);
;     LUPD(alA); RESC(alB); SBAR();
.Ldma_done:
	v_exp_f32_e32 v80, v80
	v_exp_f32_e32 v81, v81
	s_waitcnt lgkmcnt(6)
	v_mfma_scale_f32_32x32x64_f8f6f4 v[182:197], v[104:109], v[120:125], v[240:255], v162, v143 op_sel_hi:[0,0,0] cbsz:2 blgp:2
	v_exp_f32_e32 v82, v82
	v_exp_f32_e32 v83, v83
	v_exp_f32_e32 v84, v84
	v_exp_f32_e32 v85, v85
	v_mfma_scale_f32_32x32x64_f8f6f4 v[198:213], v[110:115], v[120:125], v[240:255], v162, v143 op_sel_hi:[0,0,0] cbsz:2 blgp:2
	ds_read_b128 v[104:107], v140 offset:4096
	ds_read_b128 v[108:111], v140 offset:4608
	ds_read_b128 v[112:115], v140 offset:6144
	ds_read_b128 v[116:119], v140 offset:6656
	v_exp_f32_e32 v86, v86
	s_waitcnt lgkmcnt(7)
	v_mfma_scale_f32_32x32x64_f8f6f4 v[182:197], v[148:153], v[126:131], v[182:197], v162, v143 op_sel_hi:[0,0,0] cbsz:2 blgp:2
	v_exp_f32_e32 v87, v87
	v_exp_f32_e32 v88, v88
	v_exp_f32_e32 v89, v89
	v_exp_f32_e32 v90, v90
	v_fma_f32 v180, v226, v180, v144
	v_mfma_scale_f32_32x32x64_f8f6f4 v[198:213], v[154:159], v[126:131], v[198:213], v162, v143 op_sel_hi:[0,0,0] cbsz:2 blgp:2
	ds_read_b128 v[148:151], v140 offset:8192
	ds_read_b128 v[152:155], v140 offset:8704
	v_exp_f32_e32 v91, v91
	v_exp_f32_e32 v92, v92
	s_waitcnt lgkmcnt(6)
	v_mfma_scale_f32_32x32x64_f8f6f4 v[182:197], v[214:219], v[132:137], v[182:197], v162, v143 op_sel_hi:[0,0,0] cbsz:2 blgp:2
	v_exp_f32_e32 v93, v93
	v_exp_f32_e32 v94, v94
	v_exp_f32_e32 v95, v95
	v_cvt_pk_fp8_f32 v96, v64, v65
	v_cvt_pk_fp8_f32 v97, v68, v69
	v_mfma_scale_f32_32x32x64_f8f6f4 v[198:213], v[220:225], v[132:137], v[198:213], v162, v143 op_sel_hi:[0,0,0] cbsz:2 blgp:2
	ds_read_b128 v[214:217], v140 offset:10240
	ds_read_b128 v[218:221], v140 offset:10752
	v_cvt_pk_fp8_f32 v98, v72, v73
	v_cvt_pk_fp8_f32 v99, v76, v77
	v_cvt_pk_fp8_f32 v96, v66, v67 op_sel:[0,0,1]
	v_cvt_pk_fp8_f32 v97, v70, v71 op_sel:[0,0,1]
	v_cvt_pk_fp8_f32 v98, v74, v75 op_sel:[0,0,1]
	v_cvt_pk_fp8_f32 v99, v78, v79 op_sel:[0,0,1]
	v_cvt_pk_fp8_f32 v100, v80, v81
	v_cvt_pk_fp8_f32 v101, v84, v85
	v_cvt_pk_fp8_f32 v102, v88, v89
	v_cvt_pk_fp8_f32 v103, v92, v93
	v_cvt_pk_fp8_f32 v100, v82, v83 op_sel:[0,0,1]
	v_cvt_pk_fp8_f32 v101, v86, v87 op_sel:[0,0,1]
	v_cvt_pk_fp8_f32 v102, v90, v91 op_sel:[0,0,1]
	v_cvt_pk_fp8_f32 v103, v94, v95 op_sel:[0,0,1]
	s_waitcnt lgkmcnt(2)
	s_nop 0
	v_mfma_f32_32x32x64_f8f6f4 v[0:15], v[96:103], v[104:111], v[0:15]
	v_max_f32_e32 v229, v182, v183
	v_max3_f32 v229, v229, v184, v185
	v_max3_f32 v229, v229, v186, v187
	v_max3_f32 v229, v229, v188, v189
	v_max3_f32 v229, v229, v190, v191
	v_max3_f32 v229, v229, v192, v193
	v_max3_f32 v229, v229, v194, v195
	v_max3_f32 v229, v229, v196, v197
	v_mfma_f32_32x32x64_f8f6f4 v[48:63], v[96:103], v[112:119], v[48:63]
	v_max3_f32 v229, v229, v198, v199
	v_max3_f32 v229, v229, v200, v201
	v_max3_f32 v229, v229, v202, v203
	v_max3_f32 v229, v229, v204, v205
	v_max3_f32 v229, v229, v206, v207
	v_max3_f32 v229, v229, v208, v209
	v_max3_f32 v229, v229, v210, v211
	v_max3_f32 v229, v229, v212, v213
	v_cmp_ge_f32_e32 vcc, s69, v229
	s_cmp_eq_u64 vcc, exec
	v_mov_b32_e32 v226, 1.0
	s_cbranch_scc0 .Lslow_a0
	ds_read_b128 v[104:107], v173 offset:18432
	ds_read_b128 v[108:111], v176 offset:18432
	ds_read_b128 v[112:115], v173 offset:18944
	v_mfma_f32_32x32x64_f8f6f4 v[16:31], v[96:103], v[148:155], v[16:31]
	v_exp_f32_e32 v182, v182
	v_exp_f32_e32 v183, v183
	v_exp_f32_e32 v184, v184
	v_exp_f32_e32 v185, v185
	v_exp_f32_e32 v186, v186
	v_exp_f32_e32 v187, v187
	ds_read_b128 v[148:151], v173 offset:20480
	ds_read_b128 v[152:155], v176 offset:19456
	ds_read_b128 v[156:159], v173 offset:20992
	s_waitcnt lgkmcnt(6)
	v_mfma_f32_32x32x64_f8f6f4 v[32:47], v[96:103], v[214:221], v[32:47]
	v_exp_f32_e32 v188, v188
	v_exp_f32_e32 v189, v189
	v_exp_f32_e32 v190, v190
	v_exp_f32_e32 v191, v191
	v_exp_f32_e32 v192, v192
	v_exp_f32_e32 v193, v193
	ds_read_b128 v[214:217], v173 offset:24576
	ds_read_b128 v[218:221], v176 offset:22528
	ds_read_b128 v[222:225], v173 offset:25088
	v_mfma_f32_16x16x128_f8f6f4 v[144:147], v[232:239], v[96:103], 0
	v_exp_f32_e32 v194, v194
	v_exp_f32_e32 v195, v195
	v_exp_f32_e32 v196, v196
	v_exp_f32_e32 v197, v197
; #define SBAR() __builtin_amdgcn_sched_barrier(0)
; #define PVM(db) do { const i32x8 b = {(int)f.v[db][0][0], (int)f.v[db][0][1], (int)f.v[db][0][2], (int)f.v[db][0][3], (int)f.v[db][1][0], (int)f.v[db][1][1], (int)f.v[db][1][2], (int)f.v[db][1][3]}; \
;     o[db] = MFMA8(pa, b, o[db]); } while (0)
; #define TILE_SYNC() do { asm volatile("s_waitcnt vmcnt(0)" ::: "memory"); __syncthreads(); } while (0)
; #define RESC(a) do { if (__any((a) < 1.f)) { if (hi == 0) al_l[r32] = (a); asm volatile("s_waitcnt lgkmcnt(0)" ::: "memory"); \
;     for (int d = 0; d < 4; ++d) for (int r = 0; r < 16; ++r) o[d][r] *= al_l[crow(r, hi)]; } } while (0)
; #define LUPD(al) do { l_reg = l_reg * (al) + lsum[0]; } while (0)
; DEVINL void pv_psm(f32x16* o, const VFrag& f, const i32x8& pa, f32x16& lsum, const i32x8& ones8,
;                    f32x16& p0, f32x16& p1, float& m_reg, float& mn, float& alpha, int kvalid, int hi) {
;     ...
;   PVM(1);
; #pragma unroll
;   for (int r = 0; r < 16; ++r) pmax = fmaxf(pmax, p1[r]);
;   { auto rr = __builtin_amdgcn_permlane32_swap(__float_as_uint(pmax), __float_as_uint(pmax), false, false);
;     pmax = fmaxf(__uint_as_float(rr[0]), __uint_as_float(rr[1])); }
;   SBAR();
;   PVM(2);
;   if (__builtin_expect(__all(pmax - m_reg <= THR / MLA_SCALE), 1)) { mn = m_reg; alpha = 1.f; }
;   else { mn = fmaxf(m_reg, pmax); alpha = __builtin_amdgcn_exp2f((m_reg - mn) * C); m_reg = mn; }
; DEVINL void mla_block(const Params& p, const bf16_t* __restrict__ Qn, const bf16_t* __restrict__ Qr, const char* __restrict__ K8, const char* __restrict__ Kp8,
;                       const char* __restrict__ V8, const bf16_t* __restrict__ Gb, bf16_t* __restrict__ Yb, char* lds, int pos0) {
;     ...
;     qkt<true>(pA0, pA1, KS(j + 1), q8, r32, hi, pB1);
;     pv_load(vf, VS(j), r32, hi); SBAR();
;     finishSM<true>(pB0, pB1, alB, l_reg, pa); SBAR();
;     { const float alPrev = alB; pv_psm(o, vf, pa, lsum, ones8, pA0, pA1, m_reg, mnA, alA, L - (j + 1) * KVBLK, hi); LUPD(alPrev); }
;     TILE_SYNC(); RESC(alA);
.Ljoin_a0:
	v_exp_f32_e32 v198, v198
	v_exp_f32_e32 v199, v199
	s_waitcnt lgkmcnt(6)
	v_mfma_scale_f32_32x32x64_f8f6f4 v[64:79], v[104:109], v[120:125], v[240:255], v162, v143 op_sel_hi:[0,0,0] cbsz:2 blgp:2
	v_exp_f32_e32 v200, v200
	v_exp_f32_e32 v201, v201
	v_exp_f32_e32 v202, v202
	v_exp_f32_e32 v203, v203
	v_mfma_scale_f32_32x32x64_f8f6f4 v[80:95], v[110:115], v[120:125], v[240:255], v162, v143 op_sel_hi:[0,0,0] cbsz:2 blgp:2
	ds_read_b128 v[104:107], v140 offset:12288
	ds_read_b128 v[108:111], v140 offset:12800
	ds_read_b128 v[112:115], v140 offset:14336
	ds_read_b128 v[116:119], v140 offset:14848
	v_exp_f32_e32 v204, v204
	s_waitcnt lgkmcnt(7)
	v_mfma_scale_f32_32x32x64_f8f6f4 v[64:79], v[148:153], v[126:131], v[64:79], v162, v143 op_sel_hi:[0,0,0] cbsz:2 blgp:2
	v_exp_f32_e32 v205, v205
	v_exp_f32_e32 v206, v206
	v_exp_f32_e32 v207, v207
	v_exp_f32_e32 v208, v208
	v_fma_f32 v180, v179, v180, v144
	v_mfma_scale_f32_32x32x64_f8f6f4 v[80:95], v[154:159], v[126:131], v[80:95], v162, v143 op_sel_hi:[0,0,0] cbsz:2 blgp:2
	ds_read_b128 v[148:151], v140 offset:16384
	ds_read_b128 v[152:155], v140 offset:16896
	v_exp_f32_e32 v209, v209
	v_exp_f32_e32 v210, v210
	s_waitcnt lgkmcnt(6)
	v_mfma_scale_f32_32x32x64_f8f6f4 v[64:79], v[214:219], v[132:137], v[64:79], v162, v143 op_sel_hi:[0,0,0] cbsz:2 blgp:2
	v_exp_f32_e32 v211, v211
	v_exp_f32_e32 v212, v212
	v_exp_f32_e32 v213, v213
	v_cvt_pk_fp8_f32 v96, v182, v183
	v_cvt_pk_fp8_f32 v97, v186, v187
	v_mfma_scale_f32_32x32x64_f8f6f4 v[80:95], v[220:225], v[132:137], v[80:95], v162, v143 op_sel_hi:[0,0,0] cbsz:2 blgp:2
	ds_read_b128 v[214:217], v140 offset:18432
	ds_read_b128 v[218:221], v140 offset:18944
	v_cvt_pk_fp8_f32 v98, v190, v191
	v_cvt_pk_fp8_f32 v99, v194, v195
	v_cvt_pk_fp8_f32 v96, v184, v185 op_sel:[0,0,1]
	v_cvt_pk_fp8_f32 v97, v188, v189 op_sel:[0,0,1]
	v_cvt_pk_fp8_f32 v98, v192, v193 op_sel:[0,0,1]
	v_cvt_pk_fp8_f32 v99, v196, v197 op_sel:[0,0,1]
	v_cvt_pk_fp8_f32 v100, v198, v199
	v_cvt_pk_fp8_f32 v101, v202, v203
	v_cvt_pk_fp8_f32 v102, v206, v207
	v_cvt_pk_fp8_f32 v103, v210, v211
	v_cvt_pk_fp8_f32 v100, v200, v201 op_sel:[0,0,1]
	v_cvt_pk_fp8_f32 v101, v204, v205 op_sel:[0,0,1]
	v_cvt_pk_fp8_f32 v102, v208, v209 op_sel:[0,0,1]
	v_cvt_pk_fp8_f32 v103, v212, v213 op_sel:[0,0,1]
	s_waitcnt lgkmcnt(2)
	s_nop 0
	v_mfma_f32_32x32x64_f8f6f4 v[0:15], v[96:103], v[104:111], v[0:15]
	v_max_f32_e32 v229, v64, v65
	v_max3_f32 v229, v229, v66, v67
	v_max3_f32 v229, v229, v68, v69
	v_max3_f32 v229, v229, v70, v71
	v_max3_f32 v229, v229, v72, v73
	v_max3_f32 v229, v229, v74, v75
	v_max3_f32 v229, v229, v76, v77
	v_max3_f32 v229, v229, v78, v79
	v_mfma_f32_32x32x64_f8f6f4 v[48:63], v[96:103], v[112:119], v[48:63]
	v_max3_f32 v229, v229, v80, v81
	v_max3_f32 v229, v229, v82, v83
	v_max3_f32 v229, v229, v84, v85
	v_max3_f32 v229, v229, v86, v87
	v_max3_f32 v229, v229, v88, v89
	v_max3_f32 v229, v229, v90, v91
	v_max3_f32 v229, v229, v92, v93
	v_max3_f32 v229, v229, v94, v95
	v_cmp_ge_f32_e32 vcc, s69, v229
	s_cmp_eq_u64 vcc, exec
	v_mov_b32_e32 v228, 1.0
	s_cbranch_scc0 .Lslow_b0
	s_waitcnt vmcnt(0) lgkmcnt(0)
	s_barrier
	ds_read_b128 v[104:107], v173 offset:27648
	ds_read_b128 v[108:111], v176 offset:27648
	ds_read_b128 v[112:115], v173 offset:28160
	v_mfma_f32_32x32x64_f8f6f4 v[16:31], v[96:103], v[148:155], v[16:31]
	v_exp_f32_e32 v64, v64
	v_exp_f32_e32 v65, v65
	v_exp_f32_e32 v66, v66
	v_exp_f32_e32 v67, v67
	v_exp_f32_e32 v68, v68
	v_exp_f32_e32 v69, v69
	ds_read_b128 v[148:151], v173 offset:29696
	ds_read_b128 v[152:155], v176 offset:28672
	ds_read_b128 v[156:159], v173 offset:30208
	v_mfma_f32_32x32x64_f8f6f4 v[32:47], v[96:103], v[214:221], v[32:47]
	v_exp_f32_e32 v70, v70
	v_exp_f32_e32 v71, v71
	v_exp_f32_e32 v72, v72
	v_exp_f32_e32 v73, v73
	v_exp_f32_e32 v74, v74
	v_exp_f32_e32 v75, v75
	ds_read_b128 v[214:217], v173 offset:33792
	ds_read_b128 v[218:221], v176 offset:31744
	ds_read_b128 v[222:225], v173 offset:34304
	v_mfma_f32_16x16x128_f8f6f4 v[144:147], v[232:239], v[96:103], 0
	v_exp_f32_e32 v76, v76
	v_exp_f32_e32 v77, v77
	v_exp_f32_e32 v78, v78
	v_exp_f32_e32 v79, v79

; #define SBAR() __builtin_amdgcn_sched_barrier(0)
; #define PVM(db) do { const i32x8 b = {(int)f.v[db][0][0], (int)f.v[db][0][1], (int)f.v[db][0][2], (int)f.v[db][0][3], (int)f.v[db][1][0], (int)f.v[db][1][1], (int)f.v[db][1][2], (int)f.v[db][1][3]}; \
;     o[db] = MFMA8(pa, b, o[db]); } while (0)
; #define ISSUE_K(j) do { const int _t = (j) < NT ? (j) : NT - 1; char* _d = K_lds + ((j) & 3) * SHM_K8; if (wid < 6) GLDS(K8 + (size_t)_t * 6144 + t16u, _d + tid16); \
;     if (wid < 3) GLDS(Kp8 + (size_t)_t * 3072 + t16u, _d + 6144 + tid16); } while (0)
; #define ISSUE_V(j) do { const int _t = (j) < NT ? (j) : NT - 1; GLDS(V8 + (size_t)_t * 8192 + t16u, V_lds + ((j) & 3) * SHM_V8 + tid16); } while (0)
; #define RESC(a) do { if (__any((a) < 1.f)) { if (hi == 0) al_l[r32] = (a); asm volatile("s_waitcnt lgkmcnt(0)" ::: "memory"); \
;     for (int d = 0; d < 4; ++d) for (int r = 0; r < 16; ++r) o[d][r] *= al_l[crow(r, hi)]; } } while (0)
; #define LUPD(al) do { l_reg = l_reg * (al) + lsum[0]; } while (0)
; DEVINL void pv_psm(f32x16* o, const VFrag& f, const i32x8& pa, f32x16& lsum, const i32x8& ones8,
;                    f32x16& p0, f32x16& p1, float& m_reg, float& mn, float& alpha, int kvalid, int hi) {
;     ...
;   PVM(1);
; #pragma unroll
;   for (int r = 0; r < 16; ++r) pmax = fmaxf(pmax, p1[r]);
;   { auto rr = __builtin_amdgcn_permlane32_swap(__float_as_uint(pmax), __float_as_uint(pmax), false, false);
;     pmax = fmaxf(__uint_as_float(rr[0]), __uint_as_float(rr[1])); }
;   SBAR();
;   PVM(2);
;   if (__builtin_expect(__all(pmax - m_reg <= THR / MLA_SCALE), 1)) { mn = m_reg; alpha = 1.f; }
;   else { mn = fmaxf(m_reg, pmax); alpha = __builtin_amdgcn_exp2f((m_reg - mn) * C); m_reg = mn; }
; DEVINL void mla_block(const Params& p, const bf16_t* __restrict__ Qn, const bf16_t* __restrict__ Qr, const char* __restrict__ K8, const char* __restrict__ Kp8,
;                       const char* __restrict__ V8, const bf16_t* __restrict__ Gb, bf16_t* __restrict__ Yb, char* lds, int pos0) {
;     ...
;   for (int j = 1; j + 1 < NT; j += 2) {
;     ISSUE_K(j + 2); ISSUE_K(j + 3); ISSUE_V(j + 1); ISSUE_V(j + 2); SBAR();
;     qkt<true>(pB0, pB1, KS(j), q8, r32, hi, pA1);
;     pv_load(vf, VS(j - 1), r32, hi); SBAR();
;     finishSM<true>(pA0, pA1, alA, l_reg, pa); SBAR();
;     pv_psm(o, vf, pa, lsum, ones8, pB0, pB1, m_reg, mnB, alB, 64, hi);
;     LUPD(alA); RESC(alB); SBAR();
.Lu1_dma_done:
	v_exp_f32_e32 v80, v80
	v_exp_f32_e32 v81, v81
	s_waitcnt lgkmcnt(6)
	v_mfma_scale_f32_32x32x64_f8f6f4 v[182:197], v[104:109], v[120:125], v[240:255], v162, v143 op_sel_hi:[0,0,0] cbsz:2 blgp:2
	v_exp_f32_e32 v82, v82
	v_exp_f32_e32 v83, v83
	v_exp_f32_e32 v84, v84
	v_exp_f32_e32 v85, v85
	v_mfma_scale_f32_32x32x64_f8f6f4 v[198:213], v[110:115], v[120:125], v[240:255], v162, v143 op_sel_hi:[0,0,0] cbsz:2 blgp:2
	ds_read_b128 v[104:107], v140 offset:20480
	ds_read_b128 v[108:111], v140 offset:20992
	ds_read_b128 v[112:115], v140 offset:22528
	ds_read_b128 v[116:119], v140 offset:23040
	v_exp_f32_e32 v86, v86
	s_waitcnt lgkmcnt(7)
	v_mfma_scale_f32_32x32x64_f8f6f4 v[182:197], v[148:153], v[126:131], v[182:197], v162, v143 op_sel_hi:[0,0,0] cbsz:2 blgp:2
	v_exp_f32_e32 v87, v87
	v_exp_f32_e32 v88, v88
	v_exp_f32_e32 v89, v89
	v_exp_f32_e32 v90, v90
	v_fma_f32 v180, v226, v180, v144
	v_mfma_scale_f32_32x32x64_f8f6f4 v[198:213], v[154:159], v[126:131], v[198:213], v162, v143 op_sel_hi:[0,0,0] cbsz:2 blgp:2
	ds_read_b128 v[148:151], v140 offset:24576
	ds_read_b128 v[152:155], v140 offset:25088
	v_exp_f32_e32 v91, v91
	v_exp_f32_e32 v92, v92
	s_waitcnt lgkmcnt(6)
	v_mfma_scale_f32_32x32x64_f8f6f4 v[182:197], v[214:219], v[132:137], v[182:197], v162, v143 op_sel_hi:[0,0,0] cbsz:2 blgp:2
	v_exp_f32_e32 v93, v93
	v_exp_f32_e32 v94, v94
	v_exp_f32_e32 v95, v95
	v_cvt_pk_fp8_f32 v96, v64, v65
	v_cvt_pk_fp8_f32 v97, v68, v69
	v_mfma_scale_f32_32x32x64_f8f6f4 v[198:213], v[220:225], v[132:137], v[198:213], v162, v143 op_sel_hi:[0,0,0] cbsz:2 blgp:2
	ds_read_b128 v[214:217], v140 offset:26624
	ds_read_b128 v[218:221], v140 offset:27136
	v_cvt_pk_fp8_f32 v98, v72, v73
	v_cvt_pk_fp8_f32 v99, v76, v77
	v_cvt_pk_fp8_f32 v96, v66, v67 op_sel:[0,0,1]
	v_cvt_pk_fp8_f32 v97, v70, v71 op_sel:[0,0,1]
	v_cvt_pk_fp8_f32 v98, v74, v75 op_sel:[0,0,1]
	v_cvt_pk_fp8_f32 v99, v78, v79 op_sel:[0,0,1]
	v_cvt_pk_fp8_f32 v100, v80, v81
	v_cvt_pk_fp8_f32 v101, v84, v85
	v_cvt_pk_fp8_f32 v102, v88, v89
	v_cvt_pk_fp8_f32 v103, v92, v93
	v_cvt_pk_fp8_f32 v100, v82, v83 op_sel:[0,0,1]
	v_cvt_pk_fp8_f32 v101, v86, v87 op_sel:[0,0,1]
	v_cvt_pk_fp8_f32 v102, v90, v91 op_sel:[0,0,1]
	v_cvt_pk_fp8_f32 v103, v94, v95 op_sel:[0,0,1]
	s_waitcnt lgkmcnt(2)
	s_nop 0
	v_mfma_f32_32x32x64_f8f6f4 v[0:15], v[96:103], v[104:111], v[0:15]
	v_max_f32_e32 v229, v182, v183
	v_max3_f32 v229, v229, v184, v185
	v_max3_f32 v229, v229, v186, v187
	v_max3_f32 v229, v229, v188, v189
	v_max3_f32 v229, v229, v190, v191
	v_max3_f32 v229, v229, v192, v193
	v_max3_f32 v229, v229, v194, v195
	v_max3_f32 v229, v229, v196, v197
	v_mfma_f32_32x32x64_f8f6f4 v[48:63], v[96:103], v[112:119], v[48:63]
	v_max3_f32 v229, v229, v198, v199
	v_max3_f32 v229, v229, v200, v201
	v_max3_f32 v229, v229, v202, v203
	v_max3_f32 v229, v229, v204, v205
	v_max3_f32 v229, v229, v206, v207
	v_max3_f32 v229, v229, v208, v209
	v_max3_f32 v229, v229, v210, v211
	v_max3_f32 v229, v229, v212, v213
	v_cmp_ge_f32_e32 vcc, s69, v229
	s_cmp_eq_u64 vcc, exec
	v_mov_b32_e32 v226, 1.0
	s_cbranch_scc0 .Lslow_a1
	ds_read_b128 v[104:107], v173 offset:0
	ds_read_b128 v[108:111], v176 offset:0
	ds_read_b128 v[112:115], v173 offset:512
	v_mfma_f32_32x32x64_f8f6f4 v[16:31], v[96:103], v[148:155], v[16:31]
	v_exp_f32_e32 v182, v182
	v_exp_f32_e32 v183, v183
	v_exp_f32_e32 v184, v184
	v_exp_f32_e32 v185, v185
	v_exp_f32_e32 v186, v186
	v_exp_f32_e32 v187, v187
	ds_read_b128 v[148:151], v173 offset:2048
	ds_read_b128 v[152:155], v176 offset:1024
	ds_read_b128 v[156:159], v173 offset:2560
	s_waitcnt lgkmcnt(6)
	v_mfma_f32_32x32x64_f8f6f4 v[32:47], v[96:103], v[214:221], v[32:47]
	v_exp_f32_e32 v188, v188
	v_exp_f32_e32 v189, v189
	v_exp_f32_e32 v190, v190
	v_exp_f32_e32 v191, v191
	v_exp_f32_e32 v192, v192
	v_exp_f32_e32 v193, v193
	ds_read_b128 v[214:217], v173 offset:6144
	ds_read_b128 v[218:221], v176 offset:4096
	ds_read_b128 v[222:225], v173 offset:6656
	v_mfma_f32_16x16x128_f8f6f4 v[144:147], v[232:239], v[96:103], 0
	v_exp_f32_e32 v194, v194
	v_exp_f32_e32 v195, v195
	v_exp_f32_e32 v196, v196
	v_exp_f32_e32 v197, v197
; #define SBAR() __builtin_amdgcn_sched_barrier(0)
; #define PVM(db) do { const i32x8 b = {(int)f.v[db][0][0], (int)f.v[db][0][1], (int)f.v[db][0][2], (int)f.v[db][0][3], (int)f.v[db][1][0], (int)f.v[db][1][1], (int)f.v[db][1][2], (int)f.v[db][1][3]}; \
;     o[db] = MFMA8(pa, b, o[db]); } while (0)
; #define TILE_SYNC() do { asm volatile("s_waitcnt vmcnt(0)" ::: "memory"); __syncthreads(); } while (0)
; #define RESC(a) do { if (__any((a) < 1.f)) { if (hi == 0) al_l[r32] = (a); asm volatile("s_waitcnt lgkmcnt(0)" ::: "memory"); \
;     for (int d = 0; d < 4; ++d) for (int r = 0; r < 16; ++r) o[d][r] *= al_l[crow(r, hi)]; } } while (0)
; #define LUPD(al) do { l_reg = l_reg * (al) + lsum[0]; } while (0)
; DEVINL void pv_psm(f32x16* o, const VFrag& f, const i32x8& pa, f32x16& lsum, const i32x8& ones8,
;                    f32x16& p0, f32x16& p1, float& m_reg, float& mn, float& alpha, int kvalid, int hi) {
;     ...
;   PVM(1);
; #pragma unroll
;   for (int r = 0; r < 16; ++r) pmax = fmaxf(pmax, p1[r]);
;   { auto rr = __builtin_amdgcn_permlane32_swap(__float_as_uint(pmax), __float_as_uint(pmax), false, false);
;     pmax = fmaxf(__uint_as_float(rr[0]), __uint_as_float(rr[1])); }
;   SBAR();
;   PVM(2);
;   if (__builtin_expect(__all(pmax - m_reg <= THR / MLA_SCALE), 1)) { mn = m_reg; alpha = 1.f; }
;   else { mn = fmaxf(m_reg, pmax); alpha = __builtin_amdgcn_exp2f((m_reg - mn) * C); m_reg = mn; }
; DEVINL void mla_block(const Params& p, const bf16_t* __restrict__ Qn, const bf16_t* __restrict__ Qr, const char* __restrict__ K8, const char* __restrict__ Kp8,
;                       const char* __restrict__ V8, const bf16_t* __restrict__ Gb, bf16_t* __restrict__ Yb, char* lds, int pos0) {
;     ...
;     qkt<true>(pA0, pA1, KS(j + 1), q8, r32, hi, pB1);
;     pv_load(vf, VS(j), r32, hi); SBAR();
;     finishSM<true>(pB0, pB1, alB, l_reg, pa); SBAR();
;     { const float alPrev = alB; pv_psm(o, vf, pa, lsum, ones8, pA0, pA1, m_reg, mnA, alA, L - (j + 1) * KVBLK, hi); LUPD(alPrev); }
;     TILE_SYNC(); RESC(alA);
.Ljoin_a1:
	v_exp_f32_e32 v198, v198
	v_exp_f32_e32 v199, v199
	s_waitcnt lgkmcnt(6)
	v_mfma_scale_f32_32x32x64_f8f6f4 v[64:79], v[104:109], v[120:125], v[240:255], v162, v143 op_sel_hi:[0,0,0] cbsz:2 blgp:2
	v_exp_f32_e32 v200, v200
	v_exp_f32_e32 v201, v201
	v_exp_f32_e32 v202, v202
	v_exp_f32_e32 v203, v203
	v_mfma_scale_f32_32x32x64_f8f6f4 v[80:95], v[110:115], v[120:125], v[240:255], v162, v143 op_sel_hi:[0,0,0] cbsz:2 blgp:2
	ds_read_b128 v[104:107], v140 offset:28672
	ds_read_b128 v[108:111], v140 offset:29184
	ds_read_b128 v[112:115], v140 offset:30720
	ds_read_b128 v[116:119], v140 offset:31232
	v_exp_f32_e32 v204, v204
	s_waitcnt lgkmcnt(7)
	v_mfma_scale_f32_32x32x64_f8f6f4 v[64:79], v[148:153], v[126:131], v[64:79], v162, v143 op_sel_hi:[0,0,0] cbsz:2 blgp:2
	v_exp_f32_e32 v205, v205
	v_exp_f32_e32 v206, v206
	v_exp_f32_e32 v207, v207
	v_exp_f32_e32 v208, v208
	v_fma_f32 v180, v179, v180, v144
	v_mfma_scale_f32_32x32x64_f8f6f4 v[80:95], v[154:159], v[126:131], v[80:95], v162, v143 op_sel_hi:[0,0,0] cbsz:2 blgp:2
	ds_read_b128 v[148:151], v140 offset:32768
	ds_read_b128 v[152:155], v140 offset:33280
	v_exp_f32_e32 v209, v209
	v_exp_f32_e32 v210, v210
	s_waitcnt lgkmcnt(6)
	v_mfma_scale_f32_32x32x64_f8f6f4 v[64:79], v[214:219], v[132:137], v[64:79], v162, v143 op_sel_hi:[0,0,0] cbsz:2 blgp:2
	v_exp_f32_e32 v211, v211
	v_exp_f32_e32 v212, v212
	v_exp_f32_e32 v213, v213
	v_cvt_pk_fp8_f32 v96, v182, v183
	v_cvt_pk_fp8_f32 v97, v186, v187
	v_mfma_scale_f32_32x32x64_f8f6f4 v[80:95], v[220:225], v[132:137], v[80:95], v162, v143 op_sel_hi:[0,0,0] cbsz:2 blgp:2
	ds_read_b128 v[214:217], v140 offset:34816
	ds_read_b128 v[218:221], v140 offset:35328
	v_cvt_pk_fp8_f32 v98, v190, v191
	v_cvt_pk_fp8_f32 v99, v194, v195
	v_cvt_pk_fp8_f32 v96, v184, v185 op_sel:[0,0,1]
	v_cvt_pk_fp8_f32 v97, v188, v189 op_sel:[0,0,1]
	v_cvt_pk_fp8_f32 v98, v192, v193 op_sel:[0,0,1]
	v_cvt_pk_fp8_f32 v99, v196, v197 op_sel:[0,0,1]
	v_cvt_pk_fp8_f32 v100, v198, v199
	v_cvt_pk_fp8_f32 v101, v202, v203
	v_cvt_pk_fp8_f32 v102, v206, v207
	v_cvt_pk_fp8_f32 v103, v210, v211
	v_cvt_pk_fp8_f32 v100, v200, v201 op_sel:[0,0,1]
	v_cvt_pk_fp8_f32 v101, v204, v205 op_sel:[0,0,1]
	v_cvt_pk_fp8_f32 v102, v208, v209 op_sel:[0,0,1]
	v_cvt_pk_fp8_f32 v103, v212, v213 op_sel:[0,0,1]
	s_waitcnt lgkmcnt(2)
	s_nop 0
	v_mfma_f32_32x32x64_f8f6f4 v[0:15], v[96:103], v[104:111], v[0:15]
	s_cmpk_gt_u32 s53, 0x101
	s_cbranch_scc1 .Lmask_last
	.Lmask_ret:
	v_max_f32_e32 v229, v64, v65
	v_max3_f32 v229, v229, v66, v67
	v_max3_f32 v229, v229, v68, v69
	v_max3_f32 v229, v229, v70, v71
	v_max3_f32 v229, v229, v72, v73
	v_max3_f32 v229, v229, v74, v75
	v_max3_f32 v229, v229, v76, v77
	v_max3_f32 v229, v229, v78, v79
	v_mfma_f32_32x32x64_f8f6f4 v[48:63], v[96:103], v[112:119], v[48:63]
	v_max3_f32 v229, v229, v80, v81
	v_max3_f32 v229, v229, v82, v83
	v_max3_f32 v229, v229, v84, v85
	v_max3_f32 v229, v229, v86, v87
	v_max3_f32 v229, v229, v88, v89
	v_max3_f32 v229, v229, v90, v91
	v_max3_f32 v229, v229, v92, v93
	v_max3_f32 v229, v229, v94, v95
	v_cmp_ge_f32_e32 vcc, s69, v229
	s_cmp_eq_u64 vcc, exec
	v_mov_b32_e32 v228, 1.0
	s_cbranch_scc0 .Lslow_b1
	s_waitcnt vmcnt(0) lgkmcnt(0)
	s_barrier
	ds_read_b128 v[104:107], v173 offset:9216
	ds_read_b128 v[108:111], v176 offset:9216
	ds_read_b128 v[112:115], v173 offset:9728
	v_mfma_f32_32x32x64_f8f6f4 v[16:31], v[96:103], v[148:155], v[16:31]
	v_exp_f32_e32 v64, v64
	v_exp_f32_e32 v65, v65
	v_exp_f32_e32 v66, v66
	v_exp_f32_e32 v67, v67
	v_exp_f32_e32 v68, v68
	v_exp_f32_e32 v69, v69
	ds_read_b128 v[148:151], v173 offset:11264
	ds_read_b128 v[152:155], v176 offset:10240
	ds_read_b128 v[156:159], v173 offset:11776
	v_mfma_f32_32x32x64_f8f6f4 v[32:47], v[96:103], v[214:221], v[32:47]
	v_exp_f32_e32 v70, v70
	v_exp_f32_e32 v71, v71
	v_exp_f32_e32 v72, v72
	v_exp_f32_e32 v73, v73
	v_exp_f32_e32 v74, v74
	v_exp_f32_e32 v75, v75
	ds_read_b128 v[214:217], v173 offset:15360
	ds_read_b128 v[218:221], v176 offset:13312
	ds_read_b128 v[222:225], v173 offset:15872
	v_mfma_f32_16x16x128_f8f6f4 v[144:147], v[232:239], v[96:103], 0
	v_exp_f32_e32 v76, v76
	v_exp_f32_e32 v77, v77
	v_exp_f32_e32 v78, v78
	v_exp_f32_e32 v79, v79

; DEVINL void pv_psm(f32x16* o, const VFrag& f, const i32x8& pa, f32x16& lsum, const i32x8& ones8,
;                    f32x16& p0, f32x16& p1, float& m_reg, float& mn, float& alpha, int kvalid, int hi) {
;     ...
;   if (__builtin_expect(__all(pmax - m_reg <= THR / MLA_SCALE), 1)) { mn = m_reg; alpha = 1.f; }
;   else { mn = fmaxf(m_reg, pmax); alpha = __builtin_amdgcn_exp2f((m_reg - mn) * C); m_reg = mn; }
.Lslow_a0:
	v_mfma_f32_32x32x64_f8f6f4 v[16:31], v[96:103], v[148:155], v[16:31]
	s_waitcnt lgkmcnt(0)
	v_mfma_f32_32x32x64_f8f6f4 v[32:47], v[96:103], v[214:221], v[32:47]
	v_mfma_f32_16x16x128_f8f6f4 v[144:147], v[232:239], v[96:103], 0
	v_mov_b32_e32 v160, v229
	s_nop 1
	v_permlane32_swap_b32_e32 v229, v160
	v_max_f32_e32 v229, v229, v160
	v_sub_f32_e32 v141, v229, v164
	v_max_f32_e32 v141, 0, v141
	v_exp_f32_e64 v226, -v141
	v_sub_f32_e32 v230, v230, v141
	v_mov_b32_e32 v240, v230
	v_mov_b32_e32 v241, v230
	v_mov_b32_e32 v242, v230
	v_mov_b32_e32 v243, v230
	v_mov_b32_e32 v244, v230
	v_mov_b32_e32 v245, v230
	v_mov_b32_e32 v246, v230
	v_mov_b32_e32 v247, v230
	v_mov_b32_e32 v248, v230
	v_mov_b32_e32 v249, v230
	v_mov_b32_e32 v250, v230
	v_mov_b32_e32 v251, v230
	v_mov_b32_e32 v252, v230
	v_mov_b32_e32 v253, v230
	v_mov_b32_e32 v254, v230
	v_mov_b32_e32 v255, v230
	v_sub_f32_e32 v182, v182, v141
	v_sub_f32_e32 v183, v183, v141
	v_sub_f32_e32 v184, v184, v141
	v_sub_f32_e32 v185, v185, v141
	v_sub_f32_e32 v186, v186, v141
	v_sub_f32_e32 v187, v187, v141
	v_sub_f32_e32 v188, v188, v141
	v_sub_f32_e32 v189, v189, v141
	v_sub_f32_e32 v190, v190, v141
	v_sub_f32_e32 v191, v191, v141
	v_sub_f32_e32 v192, v192, v141
	v_sub_f32_e32 v193, v193, v141
	v_sub_f32_e32 v194, v194, v141
	v_sub_f32_e32 v195, v195, v141
	v_sub_f32_e32 v196, v196, v141
	v_sub_f32_e32 v197, v197, v141
	v_sub_f32_e32 v198, v198, v141
	v_sub_f32_e32 v199, v199, v141
	v_sub_f32_e32 v200, v200, v141
	v_sub_f32_e32 v201, v201, v141
	v_sub_f32_e32 v202, v202, v141
	v_sub_f32_e32 v203, v203, v141
	v_sub_f32_e32 v204, v204, v141
	v_sub_f32_e32 v205, v205, v141
	v_sub_f32_e32 v206, v206, v141
	v_sub_f32_e32 v207, v207, v141
	v_sub_f32_e32 v208, v208, v141
	v_sub_f32_e32 v209, v209, v141
	v_sub_f32_e32 v210, v210, v141
	v_sub_f32_e32 v211, v211, v141
	v_sub_f32_e32 v212, v212, v141
	v_sub_f32_e32 v213, v213, v141
	s_and_saveexec_b64 s[16:17], s[6:7]
	ds_write_b32 v178, v226 offset:128
	s_or_b64 exec, exec, s[16:17]
	s_waitcnt lgkmcnt(0)
	v_add_u32_e32 v142, v171, v177
	ds_read_b128 v[104:107], v142 offset:224
	ds_read_b128 v[108:111], v142 offset:192
	ds_read_b128 v[112:115], v142 offset:160
	ds_read_b128 v[116:119], v142 offset:128
	s_waitcnt lgkmcnt(0)
	v_pk_mul_f32 v[12:13], v[12:13], v[104:105]
	v_pk_mul_f32 v[8:9], v[8:9], v[108:109]
	v_pk_mul_f32 v[4:5], v[4:5], v[112:113]
	v_pk_mul_f32 v[14:15], v[14:15], v[106:107]
	v_pk_mul_f32 v[10:11], v[10:11], v[110:111]
	v_pk_mul_f32 v[6:7], v[6:7], v[114:115]
	v_pk_mul_f32 v[2:3], v[2:3], v[118:119]
	v_pk_mul_f32 v[0:1], v[0:1], v[116:117]
	v_pk_mul_f32 v[60:61], v[60:61], v[104:105]
	v_pk_mul_f32 v[56:57], v[56:57], v[108:109]
	v_pk_mul_f32 v[52:53], v[52:53], v[112:113]
	v_pk_mul_f32 v[62:63], v[62:63], v[106:107]
	v_pk_mul_f32 v[58:59], v[58:59], v[110:111]
	v_pk_mul_f32 v[54:55], v[54:55], v[114:115]
	v_pk_mul_f32 v[50:51], v[50:51], v[118:119]
	v_pk_mul_f32 v[48:49], v[48:49], v[116:117]
	v_pk_mul_f32 v[28:29], v[28:29], v[104:105]
	v_pk_mul_f32 v[24:25], v[24:25], v[108:109]
	v_pk_mul_f32 v[20:21], v[20:21], v[112:113]
	v_pk_mul_f32 v[30:31], v[30:31], v[106:107]
	v_pk_mul_f32 v[26:27], v[26:27], v[110:111]
	v_pk_mul_f32 v[22:23], v[22:23], v[114:115]
	v_pk_mul_f32 v[18:19], v[18:19], v[118:119]
	v_pk_mul_f32 v[16:17], v[16:17], v[116:117]
	v_pk_mul_f32 v[44:45], v[44:45], v[104:105]
	v_pk_mul_f32 v[40:41], v[40:41], v[108:109]
	v_pk_mul_f32 v[36:37], v[36:37], v[112:113]
	v_pk_mul_f32 v[46:47], v[46:47], v[106:107]
	v_pk_mul_f32 v[42:43], v[42:43], v[110:111]
	v_pk_mul_f32 v[38:39], v[38:39], v[114:115]
	v_pk_mul_f32 v[34:35], v[34:35], v[118:119]
	v_pk_mul_f32 v[32:33], v[32:33], v[116:117]
	ds_read_b128 v[104:107], v173 offset:18432
	ds_read_b128 v[108:111], v176 offset:18432
	ds_read_b128 v[112:115], v173 offset:18944
	ds_read_b128 v[148:151], v173 offset:20480
	ds_read_b128 v[152:155], v176 offset:19456
	ds_read_b128 v[156:159], v173 offset:20992
	ds_read_b128 v[214:217], v173 offset:24576
	ds_read_b128 v[218:221], v176 offset:22528
	ds_read_b128 v[222:225], v173 offset:25088
	v_exp_f32_e32 v182, v182
	v_exp_f32_e32 v183, v183
	v_exp_f32_e32 v184, v184
	v_exp_f32_e32 v185, v185
	v_exp_f32_e32 v186, v186
	v_exp_f32_e32 v187, v187
	v_exp_f32_e32 v188, v188
	v_exp_f32_e32 v189, v189
	v_exp_f32_e32 v190, v190
	v_exp_f32_e32 v191, v191
	v_exp_f32_e32 v192, v192
	v_exp_f32_e32 v193, v193
	v_exp_f32_e32 v194, v194
	v_exp_f32_e32 v195, v195
	v_exp_f32_e32 v196, v196
	v_exp_f32_e32 v197, v197
	s_branch .Ljoin_a0
; #define SBAR() __builtin_amdgcn_sched_barrier(0)
; #define MFMA8(A, B, C) __builtin_amdgcn_mfma_scale_f32_32x32x64_f8f6f4(A, B, C, 0, 0, 0, 0x7f7f7f7f, 0, 0x7f7f7f7f)
; #define PVM(db) do { const i32x8 b = {(int)f.v[db][0][0], (int)f.v[db][0][1], (int)f.v[db][0][2], (int)f.v[db][0][3], (int)f.v[db][1][0], (int)f.v[db][1][1], (int)f.v[db][1][2], (int)f.v[db][1][3]}; \
;     o[db] = MFMA8(pa, b, o[db]); } while (0)
; DEVINL void pv_psm(f32x16* o, const VFrag& f, const i32x8& pa, f32x16& lsum, const i32x8& ones8,
;                    f32x16& p0, f32x16& p1, float& m_reg, float& mn, float& alpha, int kvalid, int hi) {
;     ...
;   { auto rr = __builtin_amdgcn_permlane32_swap(__float_as_uint(pmax), __float_as_uint(pmax), false, false);
;     pmax = fmaxf(__uint_as_float(rr[0]), __uint_as_float(rr[1])); }
;   SBAR();
;   PVM(2);
;   if (__builtin_expect(__all(pmax - m_reg <= THR / MLA_SCALE), 1)) { mn = m_reg; alpha = 1.f; }
;   else { mn = fmaxf(m_reg, pmax); alpha = __builtin_amdgcn_exp2f((m_reg - mn) * C); m_reg = mn; }
;   const float mnC = PSHIFT - mn * C;
;   const f32x2 C2 = {C, C}, M2 = {mnC, mnC};
; #pragma unroll
;   for (int r = 0; r < 16; r += 2) { f32x2 v = {p0[r], p0[r + 1]}; v = __builtin_elementwise_fma(v, C2, M2); p0[r] = v[0]; p0[r + 1] = v[1]; }
;   SBAR();
;   PVM(3);
; #pragma unroll
;   for (int r = 0; r < 16; r += 2) { f32x2 v = {p1[r], p1[r + 1]}; v = __builtin_elementwise_fma(v, C2, M2); p1[r] = v[0]; p1[r + 1] = v[1]; }
; #pragma unroll
;   for (int r = 0; r < 8; ++r) p0[r] = __builtin_amdgcn_exp2f(p0[r]);
;   SBAR();
;   lsum = MFMA8(ones8, pa, (f32x16{}));
; #pragma unroll
;   for (int r = 8; r < 16; ++r) p0[r] = __builtin_amdgcn_exp2f(p0[r]);
.Lslow_b0:
	v_mfma_f32_32x32x64_f8f6f4 v[16:31], v[96:103], v[148:155], v[16:31]
	s_waitcnt lgkmcnt(0)
	v_mfma_f32_32x32x64_f8f6f4 v[32:47], v[96:103], v[214:221], v[32:47]
	v_mfma_f32_16x16x128_f8f6f4 v[144:147], v[232:239], v[96:103], 0
	s_waitcnt vmcnt(0)
	s_barrier
	v_mov_b32_e32 v160, v229
	s_nop 1
	v_permlane32_swap_b32_e32 v229, v160
	v_max_f32_e32 v229, v229, v160
	v_sub_f32_e32 v141, v229, v164
	v_max_f32_e32 v141, 0, v141
	v_exp_f32_e64 v228, -v141
	v_sub_f32_e32 v230, v230, v141
	v_mov_b32_e32 v240, v230
	v_mov_b32_e32 v241, v230
	v_mov_b32_e32 v242, v230
	v_mov_b32_e32 v243, v230
	v_mov_b32_e32 v244, v230
	v_mov_b32_e32 v245, v230
	v_mov_b32_e32 v246, v230
	v_mov_b32_e32 v247, v230
	v_mov_b32_e32 v248, v230
	v_mov_b32_e32 v249, v230
	v_mov_b32_e32 v250, v230
	v_mov_b32_e32 v251, v230
	v_mov_b32_e32 v252, v230
	v_mov_b32_e32 v253, v230
	v_mov_b32_e32 v254, v230
	v_mov_b32_e32 v255, v230
	v_sub_f32_e32 v64, v64, v141
	v_sub_f32_e32 v65, v65, v141
	v_sub_f32_e32 v66, v66, v141
	v_sub_f32_e32 v67, v67, v141
	v_sub_f32_e32 v68, v68, v141
	v_sub_f32_e32 v69, v69, v141
	v_sub_f32_e32 v70, v70, v141
	v_sub_f32_e32 v71, v71, v141
	v_sub_f32_e32 v72, v72, v141
	v_sub_f32_e32 v73, v73, v141
	v_sub_f32_e32 v74, v74, v141
	v_sub_f32_e32 v75, v75, v141
	v_sub_f32_e32 v76, v76, v141
	v_sub_f32_e32 v77, v77, v141
	v_sub_f32_e32 v78, v78, v141
	v_sub_f32_e32 v79, v79, v141
	v_sub_f32_e32 v80, v80, v141
	v_sub_f32_e32 v81, v81, v141
	v_sub_f32_e32 v82, v82, v141
	v_sub_f32_e32 v83, v83, v141
	v_sub_f32_e32 v84, v84, v141
	v_sub_f32_e32 v85, v85, v141
	v_sub_f32_e32 v86, v86, v141
	v_sub_f32_e32 v87, v87, v141
	v_sub_f32_e32 v88, v88, v141
	v_sub_f32_e32 v89, v89, v141
	v_sub_f32_e32 v90, v90, v141
	v_sub_f32_e32 v91, v91, v141
	v_sub_f32_e32 v92, v92, v141
	v_sub_f32_e32 v93, v93, v141
	v_sub_f32_e32 v94, v94, v141
	v_sub_f32_e32 v95, v95, v141
	s_and_saveexec_b64 s[16:17], s[6:7]
	ds_write_b32 v178, v228 offset:128
	s_or_b64 exec, exec, s[16:17]
	s_waitcnt lgkmcnt(0)
	v_add_u32_e32 v142, v171, v177
	ds_read_b128 v[104:107], v142 offset:224
	ds_read_b128 v[108:111], v142 offset:192
	ds_read_b128 v[112:115], v142 offset:160
	ds_read_b128 v[116:119], v142 offset:128
	s_waitcnt lgkmcnt(0)
	v_pk_mul_f32 v[12:13], v[12:13], v[104:105]
	v_pk_mul_f32 v[8:9], v[8:9], v[108:109]
	v_pk_mul_f32 v[4:5], v[4:5], v[112:113]
	v_pk_mul_f32 v[14:15], v[14:15], v[106:107]
	v_pk_mul_f32 v[10:11], v[10:11], v[110:111]
	v_pk_mul_f32 v[6:7], v[6:7], v[114:115]
	v_pk_mul_f32 v[2:3], v[2:3], v[118:119]
	v_pk_mul_f32 v[0:1], v[0:1], v[116:117]
	v_pk_mul_f32 v[60:61], v[60:61], v[104:105]
	v_pk_mul_f32 v[56:57], v[56:57], v[108:109]
	v_pk_mul_f32 v[52:53], v[52:53], v[112:113]
	v_pk_mul_f32 v[62:63], v[62:63], v[106:107]
	v_pk_mul_f32 v[58:59], v[58:59], v[110:111]
	v_pk_mul_f32 v[54:55], v[54:55], v[114:115]
	v_pk_mul_f32 v[50:51], v[50:51], v[118:119]
	v_pk_mul_f32 v[48:49], v[48:49], v[116:117]
	v_pk_mul_f32 v[28:29], v[28:29], v[104:105]
	v_pk_mul_f32 v[24:25], v[24:25], v[108:109]
	v_pk_mul_f32 v[20:21], v[20:21], v[112:113]
	v_pk_mul_f32 v[30:31], v[30:31], v[106:107]
	v_pk_mul_f32 v[26:27], v[26:27], v[110:111]
	v_pk_mul_f32 v[22:23], v[22:23], v[114:115]
	v_pk_mul_f32 v[18:19], v[18:19], v[118:119]
	v_pk_mul_f32 v[16:17], v[16:17], v[116:117]
	v_pk_mul_f32 v[44:45], v[44:45], v[104:105]
	v_pk_mul_f32 v[40:41], v[40:41], v[108:109]
	v_pk_mul_f32 v[36:37], v[36:37], v[112:113]
	v_pk_mul_f32 v[46:47], v[46:47], v[106:107]
	v_pk_mul_f32 v[42:43], v[42:43], v[110:111]
	v_pk_mul_f32 v[38:39], v[38:39], v[114:115]
	v_pk_mul_f32 v[34:35], v[34:35], v[118:119]
	v_pk_mul_f32 v[32:33], v[32:33], v[116:117]
	ds_read_b128 v[104:107], v173 offset:27648
	ds_read_b128 v[108:111], v176 offset:27648
	ds_read_b128 v[112:115], v173 offset:28160
	ds_read_b128 v[148:151], v173 offset:29696
	ds_read_b128 v[152:155], v176 offset:28672
	ds_read_b128 v[156:159], v173 offset:30208
	ds_read_b128 v[214:217], v173 offset:33792
	ds_read_b128 v[218:221], v176 offset:31744
	ds_read_b128 v[222:225], v173 offset:34304
	v_exp_f32_e32 v64, v64
	v_exp_f32_e32 v65, v65
	v_exp_f32_e32 v66, v66
	v_exp_f32_e32 v67, v67
	v_exp_f32_e32 v68, v68
	v_exp_f32_e32 v69, v69
	v_exp_f32_e32 v70, v70
	v_exp_f32_e32 v71, v71
	v_exp_f32_e32 v72, v72
	v_exp_f32_e32 v73, v73
	v_exp_f32_e32 v74, v74
	v_exp_f32_e32 v75, v75
	v_exp_f32_e32 v76, v76
	v_exp_f32_e32 v77, v77
	v_exp_f32_e32 v78, v78
	v_exp_f32_e32 v79, v79
	s_branch .Ljoin_b0
; #define SBAR() __builtin_amdgcn_sched_barrier(0)
; #define MFMA8(A, B, C) __builtin_amdgcn_mfma_scale_f32_32x32x64_f8f6f4(A, B, C, 0, 0, 0, 0x7f7f7f7f, 0, 0x7f7f7f7f)
; #define PVM(db) do { const i32x8 b = {(int)f.v[db][0][0], (int)f.v[db][0][1], (int)f.v[db][0][2], (int)f.v[db][0][3], (int)f.v[db][1][0], (int)f.v[db][1][1], (int)f.v[db][1][2], (int)f.v[db][1][3]}; \
;     o[db] = MFMA8(pa, b, o[db]); } while (0)
; DEVINL void pv_psm(f32x16* o, const VFrag& f, const i32x8& pa, f32x16& lsum, const i32x8& ones8,
;                    f32x16& p0, f32x16& p1, float& m_reg, float& mn, float& alpha, int kvalid, int hi) {
;     ...
;   { auto rr = __builtin_amdgcn_permlane32_swap(__float_as_uint(pmax), __float_as_uint(pmax), false, false);
;     pmax = fmaxf(__uint_as_float(rr[0]), __uint_as_float(rr[1])); }
;   SBAR();
;   PVM(2);
;   if (__builtin_expect(__all(pmax - m_reg <= THR / MLA_SCALE), 1)) { mn = m_reg; alpha = 1.f; }
;   else { mn = fmaxf(m_reg, pmax); alpha = __builtin_amdgcn_exp2f((m_reg - mn) * C); m_reg = mn; }
;   const float mnC = PSHIFT - mn * C;
;   const f32x2 C2 = {C, C}, M2 = {mnC, mnC};
; #pragma unroll
;   for (int r = 0; r < 16; r += 2) { f32x2 v = {p0[r], p0[r + 1]}; v = __builtin_elementwise_fma(v, C2, M2); p0[r] = v[0]; p0[r + 1] = v[1]; }
;   SBAR();
;   PVM(3);
; #pragma unroll
;   for (int r = 0; r < 16; r += 2) { f32x2 v = {p1[r], p1[r + 1]}; v = __builtin_elementwise_fma(v, C2, M2); p1[r] = v[0]; p1[r + 1] = v[1]; }
; #pragma unroll
;   for (int r = 0; r < 8; ++r) p0[r] = __builtin_amdgcn_exp2f(p0[r]);
;   SBAR();
;   lsum = MFMA8(ones8, pa, (f32x16{}));
; #pragma unroll
;   for (int r = 8; r < 16; ++r) p0[r] = __builtin_amdgcn_exp2f(p0[r]);
.Lslow_a1:
	v_mfma_f32_32x32x64_f8f6f4 v[16:31], v[96:103], v[148:155], v[16:31]
	s_waitcnt lgkmcnt(0)
	v_mfma_f32_32x32x64_f8f6f4 v[32:47], v[96:103], v[214:221], v[32:47]
	v_mfma_f32_16x16x128_f8f6f4 v[144:147], v[232:239], v[96:103], 0
	v_mov_b32_e32 v160, v229
	s_nop 1
	v_permlane32_swap_b32_e32 v229, v160
	v_max_f32_e32 v229, v229, v160
	v_sub_f32_e32 v141, v229, v164
	v_max_f32_e32 v141, 0, v141
	v_exp_f32_e64 v226, -v141
	v_sub_f32_e32 v230, v230, v141
	v_mov_b32_e32 v240, v230
	v_mov_b32_e32 v241, v230
	v_mov_b32_e32 v242, v230
	v_mov_b32_e32 v243, v230
	v_mov_b32_e32 v244, v230
	v_mov_b32_e32 v245, v230
	v_mov_b32_e32 v246, v230
	v_mov_b32_e32 v247, v230
	v_mov_b32_e32 v248, v230
	v_mov_b32_e32 v249, v230
	v_mov_b32_e32 v250, v230
	v_mov_b32_e32 v251, v230
	v_mov_b32_e32 v252, v230
	v_mov_b32_e32 v253, v230
	v_mov_b32_e32 v254, v230
	v_mov_b32_e32 v255, v230
	v_sub_f32_e32 v182, v182, v141
	v_sub_f32_e32 v183, v183, v141
	v_sub_f32_e32 v184, v184, v141
	v_sub_f32_e32 v185, v185, v141
	v_sub_f32_e32 v186, v186, v141
	v_sub_f32_e32 v187, v187, v141
	v_sub_f32_e32 v188, v188, v141
	v_sub_f32_e32 v189, v189, v141
	v_sub_f32_e32 v190, v190, v141
	v_sub_f32_e32 v191, v191, v141
	v_sub_f32_e32 v192, v192, v141
	v_sub_f32_e32 v193, v193, v141
	v_sub_f32_e32 v194, v194, v141
	v_sub_f32_e32 v195, v195, v141
	v_sub_f32_e32 v196, v196, v141
	v_sub_f32_e32 v197, v197, v141
	v_sub_f32_e32 v198, v198, v141
	v_sub_f32_e32 v199, v199, v141
	v_sub_f32_e32 v200, v200, v141
	v_sub_f32_e32 v201, v201, v141
	v_sub_f32_e32 v202, v202, v141
	v_sub_f32_e32 v203, v203, v141
	v_sub_f32_e32 v204, v204, v141
	v_sub_f32_e32 v205, v205, v141
	v_sub_f32_e32 v206, v206, v141
	v_sub_f32_e32 v207, v207, v141
	v_sub_f32_e32 v208, v208, v141
	v_sub_f32_e32 v209, v209, v141
	v_sub_f32_e32 v210, v210, v141
	v_sub_f32_e32 v211, v211, v141
	v_sub_f32_e32 v212, v212, v141
	v_sub_f32_e32 v213, v213, v141
	s_and_saveexec_b64 s[16:17], s[6:7]
	ds_write_b32 v178, v226 offset:128
	s_or_b64 exec, exec, s[16:17]
	s_waitcnt lgkmcnt(0)
	v_add_u32_e32 v142, v171, v177
	ds_read_b128 v[104:107], v142 offset:224
	ds_read_b128 v[108:111], v142 offset:192
	ds_read_b128 v[112:115], v142 offset:160
	ds_read_b128 v[116:119], v142 offset:128
	s_waitcnt lgkmcnt(0)
	v_pk_mul_f32 v[12:13], v[12:13], v[104:105]
	v_pk_mul_f32 v[8:9], v[8:9], v[108:109]
	v_pk_mul_f32 v[4:5], v[4:5], v[112:113]
	v_pk_mul_f32 v[14:15], v[14:15], v[106:107]
	v_pk_mul_f32 v[10:11], v[10:11], v[110:111]
	v_pk_mul_f32 v[6:7], v[6:7], v[114:115]
	v_pk_mul_f32 v[2:3], v[2:3], v[118:119]
	v_pk_mul_f32 v[0:1], v[0:1], v[116:117]
	v_pk_mul_f32 v[60:61], v[60:61], v[104:105]
	v_pk_mul_f32 v[56:57], v[56:57], v[108:109]
	v_pk_mul_f32 v[52:53], v[52:53], v[112:113]
	v_pk_mul_f32 v[62:63], v[62:63], v[106:107]
	v_pk_mul_f32 v[58:59], v[58:59], v[110:111]
	v_pk_mul_f32 v[54:55], v[54:55], v[114:115]
	v_pk_mul_f32 v[50:51], v[50:51], v[118:119]
	v_pk_mul_f32 v[48:49], v[48:49], v[116:117]
	v_pk_mul_f32 v[28:29], v[28:29], v[104:105]
	v_pk_mul_f32 v[24:25], v[24:25], v[108:109]
	v_pk_mul_f32 v[20:21], v[20:21], v[112:113]
	v_pk_mul_f32 v[30:31], v[30:31], v[106:107]
	v_pk_mul_f32 v[26:27], v[26:27], v[110:111]
	v_pk_mul_f32 v[22:23], v[22:23], v[114:115]
	v_pk_mul_f32 v[18:19], v[18:19], v[118:119]
	v_pk_mul_f32 v[16:17], v[16:17], v[116:117]
	v_pk_mul_f32 v[44:45], v[44:45], v[104:105]
	v_pk_mul_f32 v[40:41], v[40:41], v[108:109]
	v_pk_mul_f32 v[36:37], v[36:37], v[112:113]
	v_pk_mul_f32 v[46:47], v[46:47], v[106:107]
	v_pk_mul_f32 v[42:43], v[42:43], v[110:111]
	v_pk_mul_f32 v[38:39], v[38:39], v[114:115]
	v_pk_mul_f32 v[34:35], v[34:35], v[118:119]
	v_pk_mul_f32 v[32:33], v[32:33], v[116:117]
	ds_read_b128 v[104:107], v173 offset:0
	ds_read_b128 v[108:111], v176 offset:0
	ds_read_b128 v[112:115], v173 offset:512
	ds_read_b128 v[148:151], v173 offset:2048
	ds_read_b128 v[152:155], v176 offset:1024
	ds_read_b128 v[156:159], v173 offset:2560
	ds_read_b128 v[214:217], v173 offset:6144
	ds_read_b128 v[218:221], v176 offset:4096
	ds_read_b128 v[222:225], v173 offset:6656
	v_exp_f32_e32 v182, v182
	v_exp_f32_e32 v183, v183
	v_exp_f32_e32 v184, v184
	v_exp_f32_e32 v185, v185
	v_exp_f32_e32 v186, v186
	v_exp_f32_e32 v187, v187
	v_exp_f32_e32 v188, v188
	v_exp_f32_e32 v189, v189
	v_exp_f32_e32 v190, v190
	v_exp_f32_e32 v191, v191
	v_exp_f32_e32 v192, v192
	v_exp_f32_e32 v193, v193
	v_exp_f32_e32 v194, v194
	v_exp_f32_e32 v195, v195
	v_exp_f32_e32 v196, v196
	v_exp_f32_e32 v197, v197
	s_branch .Ljoin_a1
; #define SBAR() __builtin_amdgcn_sched_barrier(0)
; #define MFMA8(A, B, C) __builtin_amdgcn_mfma_scale_f32_32x32x64_f8f6f4(A, B, C, 0, 0, 0, 0x7f7f7f7f, 0, 0x7f7f7f7f)
; #define PVM(db) do { const i32x8 b = {(int)f.v[db][0][0], (int)f.v[db][0][1], (int)f.v[db][0][2], (int)f.v[db][0][3], (int)f.v[db][1][0], (int)f.v[db][1][1], (int)f.v[db][1][2], (int)f.v[db][1][3]}; \
;     o[db] = MFMA8(pa, b, o[db]); } while (0)
; DEVINL void pv_psm(f32x16* o, const VFrag& f, const i32x8& pa, f32x16& lsum, const i32x8& ones8,
;                    f32x16& p0, f32x16& p1, float& m_reg, float& mn, float& alpha, int kvalid, int hi) {
;     ...
;   { auto rr = __builtin_amdgcn_permlane32_swap(__float_as_uint(pmax), __float_as_uint(pmax), false, false);
;     pmax = fmaxf(__uint_as_float(rr[0]), __uint_as_float(rr[1])); }
;   SBAR();
;   PVM(2);
;   if (__builtin_expect(__all(pmax - m_reg <= THR / MLA_SCALE), 1)) { mn = m_reg; alpha = 1.f; }
;   else { mn = fmaxf(m_reg, pmax); alpha = __builtin_amdgcn_exp2f((m_reg - mn) * C); m_reg = mn; }
;   const float mnC = PSHIFT - mn * C;
;   const f32x2 C2 = {C, C}, M2 = {mnC, mnC};
; #pragma unroll
;   for (int r = 0; r < 16; r += 2) { f32x2 v = {p0[r], p0[r + 1]}; v = __builtin_elementwise_fma(v, C2, M2); p0[r] = v[0]; p0[r + 1] = v[1]; }
;   SBAR();
;   PVM(3);
; #pragma unroll
;   for (int r = 0; r < 16; r += 2) { f32x2 v = {p1[r], p1[r + 1]}; v = __builtin_elementwise_fma(v, C2, M2); p1[r] = v[0]; p1[r + 1] = v[1]; }
; #pragma unroll
;   for (int r = 0; r < 8; ++r) p0[r] = __builtin_amdgcn_exp2f(p0[r]);
;   SBAR();
;   lsum = MFMA8(ones8, pa, (f32x16{}));
; #pragma unroll
;   for (int r = 8; r < 16; ++r) p0[r] = __builtin_amdgcn_exp2f(p0[r]);
.Lslow_b1:
	v_mfma_f32_32x32x64_f8f6f4 v[16:31], v[96:103], v[148:155], v[16:31]
	s_waitcnt lgkmcnt(0)
	v_mfma_f32_32x32x64_f8f6f4 v[32:47], v[96:103], v[214:221], v[32:47]
	v_mfma_f32_16x16x128_f8f6f4 v[144:147], v[232:239], v[96:103], 0
	s_waitcnt vmcnt(0)
	s_barrier
	v_mov_b32_e32 v160, v229
	s_nop 1
	v_permlane32_swap_b32_e32 v229, v160
	v_max_f32_e32 v229, v229, v160
	v_sub_f32_e32 v141, v229, v164
	v_max_f32_e32 v141, 0, v141
	v_exp_f32_e64 v228, -v141
	v_sub_f32_e32 v230, v230, v141
	v_mov_b32_e32 v240, v230
	v_mov_b32_e32 v241, v230
	v_mov_b32_e32 v242, v230
	v_mov_b32_e32 v243, v230
	v_mov_b32_e32 v244, v230
	v_mov_b32_e32 v245, v230
	v_mov_b32_e32 v246, v230
	v_mov_b32_e32 v247, v230
	v_mov_b32_e32 v248, v230
	v_mov_b32_e32 v249, v230
	v_mov_b32_e32 v250, v230
	v_mov_b32_e32 v251, v230
	v_mov_b32_e32 v252, v230
	v_mov_b32_e32 v253, v230
	v_mov_b32_e32 v254, v230
	v_mov_b32_e32 v255, v230
	v_sub_f32_e32 v64, v64, v141
	v_sub_f32_e32 v65, v65, v141
	v_sub_f32_e32 v66, v66, v141
	v_sub_f32_e32 v67, v67, v141
	v_sub_f32_e32 v68, v68, v141
	v_sub_f32_e32 v69, v69, v141
	v_sub_f32_e32 v70, v70, v141
	v_sub_f32_e32 v71, v71, v141
	v_sub_f32_e32 v72, v72, v141
	v_sub_f32_e32 v73, v73, v141
	v_sub_f32_e32 v74, v74, v141
	v_sub_f32_e32 v75, v75, v141
	v_sub_f32_e32 v76, v76, v141
	v_sub_f32_e32 v77, v77, v141
	v_sub_f32_e32 v78, v78, v141
	v_sub_f32_e32 v79, v79, v141
	v_sub_f32_e32 v80, v80, v141
	v_sub_f32_e32 v81, v81, v141
	v_sub_f32_e32 v82, v82, v141
	v_sub_f32_e32 v83, v83, v141
	v_sub_f32_e32 v84, v84, v141
	v_sub_f32_e32 v85, v85, v141
	v_sub_f32_e32 v86, v86, v141
	v_sub_f32_e32 v87, v87, v141
	v_sub_f32_e32 v88, v88, v141
	v_sub_f32_e32 v89, v89, v141
	v_sub_f32_e32 v90, v90, v141
	v_sub_f32_e32 v91, v91, v141
	v_sub_f32_e32 v92, v92, v141
	v_sub_f32_e32 v93, v93, v141
	v_sub_f32_e32 v94, v94, v141
	v_sub_f32_e32 v95, v95, v141
	s_and_saveexec_b64 s[16:17], s[6:7]
	ds_write_b32 v178, v228 offset:128
	s_or_b64 exec, exec, s[16:17]
	s_waitcnt lgkmcnt(0)
	v_add_u32_e32 v142, v171, v177
	ds_read_b128 v[104:107], v142 offset:224
	ds_read_b128 v[108:111], v142 offset:192
	ds_read_b128 v[112:115], v142 offset:160
	ds_read_b128 v[116:119], v142 offset:128
	s_waitcnt lgkmcnt(0)
	v_pk_mul_f32 v[12:13], v[12:13], v[104:105]
	v_pk_mul_f32 v[8:9], v[8:9], v[108:109]
	v_pk_mul_f32 v[4:5], v[4:5], v[112:113]
	v_pk_mul_f32 v[14:15], v[14:15], v[106:107]
	v_pk_mul_f32 v[10:11], v[10:11], v[110:111]
	v_pk_mul_f32 v[6:7], v[6:7], v[114:115]
	v_pk_mul_f32 v[2:3], v[2:3], v[118:119]
	v_pk_mul_f32 v[0:1], v[0:1], v[116:117]
	v_pk_mul_f32 v[60:61], v[60:61], v[104:105]
	v_pk_mul_f32 v[56:57], v[56:57], v[108:109]
	v_pk_mul_f32 v[52:53], v[52:53], v[112:113]
	v_pk_mul_f32 v[62:63], v[62:63], v[106:107]
	v_pk_mul_f32 v[58:59], v[58:59], v[110:111]
	v_pk_mul_f32 v[54:55], v[54:55], v[114:115]
	v_pk_mul_f32 v[50:51], v[50:51], v[118:119]
	v_pk_mul_f32 v[48:49], v[48:49], v[116:117]
	v_pk_mul_f32 v[28:29], v[28:29], v[104:105]
	v_pk_mul_f32 v[24:25], v[24:25], v[108:109]
	v_pk_mul_f32 v[20:21], v[20:21], v[112:113]
	v_pk_mul_f32 v[30:31], v[30:31], v[106:107]
	v_pk_mul_f32 v[26:27], v[26:27], v[110:111]
	v_pk_mul_f32 v[22:23], v[22:23], v[114:115]
	v_pk_mul_f32 v[18:19], v[18:19], v[118:119]
	v_pk_mul_f32 v[16:17], v[16:17], v[116:117]
	v_pk_mul_f32 v[44:45], v[44:45], v[104:105]
	v_pk_mul_f32 v[40:41], v[40:41], v[108:109]
	v_pk_mul_f32 v[36:37], v[36:37], v[112:113]
	v_pk_mul_f32 v[46:47], v[46:47], v[106:107]
	v_pk_mul_f32 v[42:43], v[42:43], v[110:111]
	v_pk_mul_f32 v[38:39], v[38:39], v[114:115]
	v_pk_mul_f32 v[34:35], v[34:35], v[118:119]
	v_pk_mul_f32 v[32:33], v[32:33], v[116:117]
	ds_read_b128 v[104:107], v173 offset:9216
	ds_read_b128 v[108:111], v176 offset:9216
	ds_read_b128 v[112:115], v173 offset:9728
	ds_read_b128 v[148:151], v173 offset:11264
	ds_read_b128 v[152:155], v176 offset:10240
	ds_read_b128 v[156:159], v173 offset:11776
	ds_read_b128 v[214:217], v173 offset:15360
	ds_read_b128 v[218:221], v176 offset:13312
	ds_read_b128 v[222:225], v173 offset:15872
	v_exp_f32_e32 v64, v64
	v_exp_f32_e32 v65, v65
	v_exp_f32_e32 v66, v66
	v_exp_f32_e32 v67, v67
	v_exp_f32_e32 v68, v68
	v_exp_f32_e32 v69, v69
	v_exp_f32_e32 v70, v70
	v_exp_f32_e32 v71, v71
	v_exp_f32_e32 v72, v72
	v_exp_f32_e32 v73, v73
	v_exp_f32_e32 v74, v74
	v_exp_f32_e32 v75, v75
	v_exp_f32_e32 v76, v76
	v_exp_f32_e32 v77, v77
	v_exp_f32_e32 v78, v78
	v_exp_f32_e32 v79, v79
	s_branch .Ljoin_b1
